# final LayerNorm pass hand-written: LN parameters hoisted out of the row loop (the per-row parameter loads forced a full vmcnt(0) right after the next row's prefetch), rows fetched three ahead in a fou
# speedup vs baseline: 1.0226x; 1.0089x over previous
.LBB0_1166:
	s_or_b64 exec, exec, s[0:1]
	s_waitcnt lgkmcnt(0)
	s_barrier
	s_cmp_eq_u32 s96, 0x100
	s_cbranch_scc1 .Lln2_hand
	s_mov_b32 s3, 0x10000
	s_waitcnt vmcnt(2)
	v_lshlrev_b32_e32 v0, 3, v200
	v_and_b32_e32 v35, 0x1f8, v0
	v_lshlrev_b32_e32 v34, 2, v35
	global_load_dwordx4 v[0:3], v34, s[78:79] offset:16
	global_load_dwordx4 v[4:7], v34, s[80:81] offset:16
	global_load_dwordx4 v[8:11], v34, s[78:79]
	global_load_dwordx4 v[12:15], v34, s[80:81]
	global_load_dwordx4 v[16:19], v34, s[78:79] offset:2064
	global_load_dwordx4 v[20:23], v34, s[80:81] offset:2064
	global_load_dwordx4 v[24:27], v34, s[78:79] offset:2048
	global_load_dwordx4 v[28:31], v34, s[80:81] offset:2048
	s_waitcnt vmcnt(8)
	v_ashrrev_i32_e32 v108, 6, v200
	v_add_u32_e32 v32, s73, v108
	v_mov_b32_e32 v37, 0
	v_cmp_gt_i32_e32 vcc, s3, v32
	v_ashrrev_i32_e32 v33, 31, v32
	v_lshlrev_b32_e32 v36, 1, v35
	s_and_saveexec_b64 s[0:1], vcc
	s_cbranch_execz .LBB0_1168
	v_lshlrev_b64 v[38:39], 11, v[32:33]
	v_lshl_add_u64 v[40:41], s[10:11], 0, v[38:39]
	v_lshl_add_u64 v[38:39], s[28:29], 0, v[38:39]
	v_lshl_add_u64 v[40:41], v[40:41], 0, v[36:37]
	v_lshl_add_u64 v[38:39], v[38:39], 0, v[36:37]
	global_load_dwordx4 v[68:71], v[40:41], off
	global_load_dwordx4 v[64:67], v[40:41], off offset:1024
	global_load_dwordx4 v[76:79], v[38:39], off
	global_load_dwordx4 v[72:75], v[38:39], off offset:1024
	v_lshl_add_u64 v[38:39], v[32:33], 3, s[4:5]
	global_load_dwordx2 v[100:101], v[38:39], off

.Lln2_hand:
	s_mov_b64 exec, -1
	v_and_b32_e32 v1, 63, v200
	v_lshrrev_b32_e32 v2, 6, v200
	s_lshl_b32 s0, s2, 3
	v_add_u32_e32 v2, s0, v2
	v_lshlrev_b32_e32 v250, 5, v1
	v_lshlrev_b32_e32 v251, 4, v1
	global_load_dwordx4 v[128:131], v250, s[78:79]
	global_load_dwordx4 v[144:147], v250, s[80:81]
	global_load_dwordx4 v[160:163], v250, s[20:21]
	global_load_dwordx4 v[176:179], v250, s[22:23]
	global_load_dwordx4 v[132:135], v250, s[78:79] offset:16
	global_load_dwordx4 v[148:151], v250, s[80:81] offset:16
	global_load_dwordx4 v[164:167], v250, s[20:21] offset:16
	global_load_dwordx4 v[180:183], v250, s[22:23] offset:16
	global_load_dwordx4 v[136:139], v250, s[78:79] offset:2048
	global_load_dwordx4 v[152:155], v250, s[80:81] offset:2048
	global_load_dwordx4 v[168:171], v250, s[20:21] offset:2048
	global_load_dwordx4 v[184:187], v250, s[22:23] offset:2048
	global_load_dwordx4 v[140:143], v250, s[78:79] offset:2064
	global_load_dwordx4 v[156:159], v250, s[80:81] offset:2064
	global_load_dwordx4 v[172:175], v250, s[20:21] offset:2064
	global_load_dwordx4 v[188:191], v250, s[22:23] offset:2064
	v_mov_b32_e32 v3, 0
	v_lshlrev_b32_e32 v4, 11, v2
	v_add_u32_e32 v4, v4, v251
	v_mov_b32_e32 v5, 0
	s_add_u32 s44, s26, 0x11000000
	s_addc_u32 s45, s27, 0
	v_lshl_add_u64 v[232:233], s[44:45], 0, v[4:5]
	s_add_u32 s44, s26, 0x1000000
	s_addc_u32 s45, s27, 0
	v_lshl_add_u64 v[234:235], s[44:45], 0, v[4:5]
	v_lshlrev_b32_e32 v4, 3, v2
	s_add_u32 s44, s26, 0x2b300000
	s_addc_u32 s45, s27, 0
	v_lshl_add_u64 v[236:237], s[44:45], 0, v[4:5]
	v_lshlrev_b32_e32 v4, 12, v2
	v_add_u32_e32 v4, v4, v250
	v_lshl_add_u64 v[238:239], s[24:25], 0, v[4:5]
	s_mov_b32 s40, 0x400000
	s_mov_b32 s42, 0x4000
	s_mov_b32 s14, 0x3f9837f0
	global_load_dwordx4 v[48:51], v[232:233], off
	global_load_dwordx4 v[52:55], v[232:233], off offset:1024
	global_load_dwordx4 v[56:59], v[234:235], off
	global_load_dwordx4 v[60:63], v[234:235], off offset:1024
	global_load_dwordx2 v[64:65], v[236:237], off
	s_mov_b32 s44, s40
	s_mov_b32 s46, s42
	s_mov_b32 s45, 0
	s_mov_b32 s47, 0
	v_lshl_add_u64 v[232:233], v[232:233], 0, s[44:45]
	v_lshl_add_u64 v[234:235], v[234:235], 0, s[44:45]
	v_lshl_add_u64 v[236:237], v[236:237], 0, s[46:47]
	global_load_dwordx4 v[68:71], v[232:233], off
	global_load_dwordx4 v[72:75], v[232:233], off offset:1024
	global_load_dwordx4 v[76:79], v[234:235], off
	global_load_dwordx4 v[80:83], v[234:235], off offset:1024
	global_load_dwordx2 v[84:85], v[236:237], off
	s_mov_b32 s44, s40
	s_mov_b32 s46, s42
	s_mov_b32 s45, 0
	s_mov_b32 s47, 0
	v_lshl_add_u64 v[232:233], v[232:233], 0, s[44:45]
	v_lshl_add_u64 v[234:235], v[234:235], 0, s[44:45]
	v_lshl_add_u64 v[236:237], v[236:237], 0, s[46:47]
	global_load_dwordx4 v[88:91], v[232:233], off
	global_load_dwordx4 v[92:95], v[232:233], off offset:1024
	global_load_dwordx4 v[96:99], v[234:235], off
	global_load_dwordx4 v[100:103], v[234:235], off offset:1024
	global_load_dwordx2 v[104:105], v[236:237], off
	s_mov_b32 s44, s40
	s_mov_b32 s46, s42
	s_mov_b32 s45, 0
	s_mov_b32 s47, 0
	v_lshl_add_u64 v[232:233], v[232:233], 0, s[44:45]
	v_lshl_add_u64 v[234:235], v[234:235], 0, s[44:45]
	v_lshl_add_u64 v[236:237], v[236:237], 0, s[46:47]
	s_waitcnt vmcnt(0)
	s_mov_b32 s33, 0
.Lln2_loop:
	global_load_dwordx4 v[108:111], v[232:233], off
	global_load_dwordx4 v[112:115], v[232:233], off offset:1024
	global_load_dwordx4 v[116:119], v[234:235], off
	global_load_dwordx4 v[120:123], v[234:235], off offset:1024
	global_load_dwordx2 v[124:125], v[236:237], off
	s_cmp_lt_u32 s33, 28
	s_cselect_b32 s44, s40, 0
	s_cselect_b32 s46, s42, 0
	s_mov_b32 s45, 0
	s_mov_b32 s47, 0
	v_lshl_add_u64 v[232:233], v[232:233], 0, s[44:45]
	v_lshl_add_u64 v[234:235], v[234:235], 0, s[44:45]
	v_lshl_add_u64 v[236:237], v[236:237], 0, s[46:47]
	s_waitcnt vmcnt(18)
	v_lshlrev_b32_e32 v16, 16, v56
	v_and_b32_e32 v17, 0xffff0000, v56
	v_lshlrev_b32_e32 v0, 16, v48
	v_and_b32_e32 v1, 0xffff0000, v48
	v_sub_f32_e32 v16, v16, v64
	v_sub_f32_e32 v17, v17, v64
	v_mul_f32_e32 v16, v16, v65
	v_mul_f32_e32 v17, v17, v65
	v_fma_f32 v16, v16, v128, v144
	v_fma_f32 v17, v17, v129, v145
	v_fma_f32 v0, v16, s14, v0
	v_fma_f32 v1, v17, s14, v1
	v_lshlrev_b32_e32 v18, 16, v57
	v_and_b32_e32 v19, 0xffff0000, v57
	v_lshlrev_b32_e32 v2, 16, v49
	v_and_b32_e32 v3, 0xffff0000, v49
	v_sub_f32_e32 v18, v18, v64
	v_sub_f32_e32 v19, v19, v64
	v_mul_f32_e32 v18, v18, v65
	v_mul_f32_e32 v19, v19, v65
	v_fma_f32 v18, v18, v130, v146
	v_fma_f32 v19, v19, v131, v147
	v_fma_f32 v2, v18, s14, v2
	v_fma_f32 v3, v19, s14, v3
	v_lshlrev_b32_e32 v20, 16, v58
	v_and_b32_e32 v21, 0xffff0000, v58
	v_lshlrev_b32_e32 v4, 16, v50
	v_and_b32_e32 v5, 0xffff0000, v50
	v_sub_f32_e32 v20, v20, v64
	v_sub_f32_e32 v21, v21, v64
	v_mul_f32_e32 v20, v20, v65
	v_mul_f32_e32 v21, v21, v65
	v_fma_f32 v20, v20, v132, v148
	v_fma_f32 v21, v21, v133, v149
	v_fma_f32 v4, v20, s14, v4
	v_fma_f32 v5, v21, s14, v5
	v_lshlrev_b32_e32 v22, 16, v59
	v_and_b32_e32 v23, 0xffff0000, v59
	v_lshlrev_b32_e32 v6, 16, v51
	v_and_b32_e32 v7, 0xffff0000, v51
	v_sub_f32_e32 v22, v22, v64
	v_sub_f32_e32 v23, v23, v64
	v_mul_f32_e32 v22, v22, v65
	v_mul_f32_e32 v23, v23, v65
	v_fma_f32 v22, v22, v134, v150
	v_fma_f32 v23, v23, v135, v151
	v_fma_f32 v6, v22, s14, v6
	v_fma_f32 v7, v23, s14, v7
	v_lshlrev_b32_e32 v24, 16, v60
	v_and_b32_e32 v25, 0xffff0000, v60
	v_lshlrev_b32_e32 v8, 16, v52
	v_and_b32_e32 v9, 0xffff0000, v52
	v_sub_f32_e32 v24, v24, v64
	v_sub_f32_e32 v25, v25, v64
	v_mul_f32_e32 v24, v24, v65
	v_mul_f32_e32 v25, v25, v65
	v_fma_f32 v24, v24, v136, v152
	v_fma_f32 v25, v25, v137, v153
	v_fma_f32 v8, v24, s14, v8
	v_fma_f32 v9, v25, s14, v9
	v_lshlrev_b32_e32 v26, 16, v61
	v_and_b32_e32 v27, 0xffff0000, v61
	v_lshlrev_b32_e32 v10, 16, v53
	v_and_b32_e32 v11, 0xffff0000, v53
	v_sub_f32_e32 v26, v26, v64
	v_sub_f32_e32 v27, v27, v64
	v_mul_f32_e32 v26, v26, v65
	v_mul_f32_e32 v27, v27, v65
	v_fma_f32 v26, v26, v138, v154
	v_fma_f32 v27, v27, v139, v155
	v_fma_f32 v10, v26, s14, v10
	v_fma_f32 v11, v27, s14, v11
	v_lshlrev_b32_e32 v28, 16, v62
	v_and_b32_e32 v29, 0xffff0000, v62
	v_lshlrev_b32_e32 v12, 16, v54
	v_and_b32_e32 v13, 0xffff0000, v54
	v_sub_f32_e32 v28, v28, v64
	v_sub_f32_e32 v29, v29, v64
	v_mul_f32_e32 v28, v28, v65
	v_mul_f32_e32 v29, v29, v65
	v_fma_f32 v28, v28, v140, v156
	v_fma_f32 v29, v29, v141, v157
	v_fma_f32 v12, v28, s14, v12
	v_fma_f32 v13, v29, s14, v13
	v_lshlrev_b32_e32 v30, 16, v63
	v_and_b32_e32 v31, 0xffff0000, v63
	v_lshlrev_b32_e32 v14, 16, v55
	v_and_b32_e32 v15, 0xffff0000, v55
	v_sub_f32_e32 v30, v30, v64
	v_sub_f32_e32 v31, v31, v64
	v_mul_f32_e32 v30, v30, v65
	v_mul_f32_e32 v31, v31, v65
	v_fma_f32 v30, v30, v142, v158
	v_fma_f32 v31, v31, v143, v159
	v_fma_f32 v14, v30, s14, v14
	v_fma_f32 v15, v31, s14, v15
	v_add_f32_e32 v16, v0, v1
	v_add_f32_e32 v17, v2, v3
	v_add_f32_e32 v18, v4, v5
	v_add_f32_e32 v19, v6, v7
	v_add_f32_e32 v20, v8, v9
	v_add_f32_e32 v21, v10, v11
	v_add_f32_e32 v22, v12, v13
	v_add_f32_e32 v23, v14, v15
	v_add_f32_e32 v16, v16, v17
	v_add_f32_e32 v18, v18, v19
	v_add_f32_e32 v20, v20, v21
	v_add_f32_e32 v22, v22, v23
	v_add_f32_e32 v16, v16, v18
	v_add_f32_e32 v20, v20, v22
	v_add_f32_e32 v32, v16, v20
	v_mov_b32_e32 v34, v32
	s_nop 1
	v_add_f32_dpp v34, v32, v32 quad_perm:[1,0,3,2] row_mask:0xf bank_mask:0xf
	s_nop 1
	v_add_f32_dpp v34, v34, v34 quad_perm:[2,3,0,1] row_mask:0xf bank_mask:0xf
	s_nop 1
	v_add_f32_dpp v34, v34, v34 row_half_mirror row_mask:0xf bank_mask:0xf
	s_nop 1
	v_add_f32_dpp v34, v34, v34 row_mirror row_mask:0xf bank_mask:0xf
	s_nop 1
	v_add_f32_dpp v34, v34, v34 row_bcast:15 row_mask:0xa bank_mask:0xf
	s_nop 1
	v_add_f32_dpp v34, v34, v34 row_bcast:31 row_mask:0xc bank_mask:0xf
	s_nop 1
	v_readlane_b32 s0, v34, 63
	s_nop 0
	v_mov_b32_e32 v33, 0x3a800000
	v_mul_f32_e32 v33, s0, v33
	v_sub_f32_e32 v0, v0, v33
	v_sub_f32_e32 v1, v1, v33
	v_sub_f32_e32 v2, v2, v33
	v_sub_f32_e32 v3, v3, v33
	v_sub_f32_e32 v4, v4, v33
	v_sub_f32_e32 v5, v5, v33
	v_sub_f32_e32 v6, v6, v33
	v_sub_f32_e32 v7, v7, v33
	v_sub_f32_e32 v8, v8, v33
	v_sub_f32_e32 v9, v9, v33
	v_sub_f32_e32 v10, v10, v33
	v_sub_f32_e32 v11, v11, v33
	v_sub_f32_e32 v12, v12, v33
	v_sub_f32_e32 v13, v13, v33
	v_sub_f32_e32 v14, v14, v33
	v_sub_f32_e32 v15, v15, v33
	v_mul_f32_e32 v16, v0, v0
	v_fmac_f32_e32 v16, v1, v1
	v_mul_f32_e32 v17, v2, v2
	v_fmac_f32_e32 v17, v3, v3
	v_mul_f32_e32 v18, v4, v4
	v_fmac_f32_e32 v18, v5, v5
	v_mul_f32_e32 v19, v6, v6
	v_fmac_f32_e32 v19, v7, v7
	v_mul_f32_e32 v20, v8, v8
	v_fmac_f32_e32 v20, v9, v9
	v_mul_f32_e32 v21, v10, v10
	v_fmac_f32_e32 v21, v11, v11
	v_mul_f32_e32 v22, v12, v12
	v_fmac_f32_e32 v22, v13, v13
	v_mul_f32_e32 v23, v14, v14
	v_fmac_f32_e32 v23, v15, v15
	v_add_f32_e32 v16, v16, v17
	v_add_f32_e32 v18, v18, v19
	v_add_f32_e32 v20, v20, v21
	v_add_f32_e32 v22, v22, v23
	v_add_f32_e32 v16, v16, v18
	v_add_f32_e32 v20, v20, v22
	v_add_f32_e32 v32, v16, v20
	v_mov_b32_e32 v34, v32
	s_nop 1
	v_add_f32_dpp v34, v32, v32 quad_perm:[1,0,3,2] row_mask:0xf bank_mask:0xf
	s_nop 1
	v_add_f32_dpp v34, v34, v34 quad_perm:[2,3,0,1] row_mask:0xf bank_mask:0xf
	s_nop 1
	v_add_f32_dpp v34, v34, v34 row_half_mirror row_mask:0xf bank_mask:0xf
	s_nop 1
	v_add_f32_dpp v34, v34, v34 row_mirror row_mask:0xf bank_mask:0xf
	s_nop 1
	v_add_f32_dpp v34, v34, v34 row_bcast:15 row_mask:0xa bank_mask:0xf
	s_nop 1
	v_add_f32_dpp v34, v34, v34 row_bcast:31 row_mask:0xc bank_mask:0xf
	s_nop 1
	v_readlane_b32 s0, v34, 63
	s_nop 0
	v_mov_b32_e32 v33, 0x3a800000
	v_mov_b32_e32 v35, 0x3727c5ac
	v_fma_f32 v33, s0, v33, v35
	v_rsq_f32_e32 v33, v33
	s_nop 0
	v_mul_f32_e32 v0, v0, v33
	v_mul_f32_e32 v1, v1, v33
	v_mul_f32_e32 v2, v2, v33
	v_mul_f32_e32 v3, v3, v33
	v_fma_f32 v0, v0, v160, v176
	v_fma_f32 v1, v1, v161, v177
	v_fma_f32 v2, v2, v162, v178
	v_fma_f32 v3, v3, v163, v179
	v_mul_f32_e32 v4, v4, v33
	v_mul_f32_e32 v5, v5, v33
	v_mul_f32_e32 v6, v6, v33
	v_mul_f32_e32 v7, v7, v33
	v_fma_f32 v4, v4, v164, v180
	v_fma_f32 v5, v5, v165, v181
	v_fma_f32 v6, v6, v166, v182
	v_fma_f32 v7, v7, v167, v183
	v_mul_f32_e32 v8, v8, v33
	v_mul_f32_e32 v9, v9, v33
	v_mul_f32_e32 v10, v10, v33
	v_mul_f32_e32 v11, v11, v33
	v_fma_f32 v8, v8, v168, v184
	v_fma_f32 v9, v9, v169, v185
	v_fma_f32 v10, v10, v170, v186
	v_fma_f32 v11, v11, v171, v187
	v_mul_f32_e32 v12, v12, v33
	v_mul_f32_e32 v13, v13, v33
	v_mul_f32_e32 v14, v14, v33
	v_mul_f32_e32 v15, v15, v33
	v_fma_f32 v12, v12, v172, v188
	v_fma_f32 v13, v13, v173, v189
	v_fma_f32 v14, v14, v174, v190
	v_fma_f32 v15, v15, v175, v191
	global_store_dwordx4 v[238:239], v[0:3], off
	global_store_dwordx4 v[238:239], v[4:7], off offset:16
	global_store_dwordx4 v[238:239], v[8:11], off offset:2048
	global_store_dwordx4 v[238:239], v[12:15], off offset:2064
	s_mov_b32 s44, 0x800000
	s_mov_b32 s45, 0
	v_lshl_add_u64 v[238:239], v[238:239], 0, s[44:45]
	s_add_u32 s33, s33, 1
	global_load_dwordx4 v[48:51], v[232:233], off
	global_load_dwordx4 v[52:55], v[232:233], off offset:1024
	global_load_dwordx4 v[56:59], v[234:235], off
	global_load_dwordx4 v[60:63], v[234:235], off offset:1024
	global_load_dwordx2 v[64:65], v[236:237], off
	s_cmp_lt_u32 s33, 28
	s_cselect_b32 s44, s40, 0
	s_cselect_b32 s46, s42, 0
	s_mov_b32 s45, 0
	s_mov_b32 s47, 0
	v_lshl_add_u64 v[232:233], v[232:233], 0, s[44:45]
	v_lshl_add_u64 v[234:235], v[234:235], 0, s[44:45]
	v_lshl_add_u64 v[236:237], v[236:237], 0, s[46:47]
	s_waitcnt vmcnt(18)
	v_lshlrev_b32_e32 v16, 16, v76
	v_and_b32_e32 v17, 0xffff0000, v76
	v_lshlrev_b32_e32 v0, 16, v68
	v_and_b32_e32 v1, 0xffff0000, v68
	v_sub_f32_e32 v16, v16, v84
	v_sub_f32_e32 v17, v17, v84
	v_mul_f32_e32 v16, v16, v85
	v_mul_f32_e32 v17, v17, v85
	v_fma_f32 v16, v16, v128, v144
	v_fma_f32 v17, v17, v129, v145
	v_fma_f32 v0, v16, s14, v0
	v_fma_f32 v1, v17, s14, v1
	v_lshlrev_b32_e32 v18, 16, v77
	v_and_b32_e32 v19, 0xffff0000, v77
	v_lshlrev_b32_e32 v2, 16, v69
	v_and_b32_e32 v3, 0xffff0000, v69
	v_sub_f32_e32 v18, v18, v84
	v_sub_f32_e32 v19, v19, v84
	v_mul_f32_e32 v18, v18, v85
	v_mul_f32_e32 v19, v19, v85
	v_fma_f32 v18, v18, v130, v146
	v_fma_f32 v19, v19, v131, v147
	v_fma_f32 v2, v18, s14, v2
	v_fma_f32 v3, v19, s14, v3
	v_lshlrev_b32_e32 v20, 16, v78
	v_and_b32_e32 v21, 0xffff0000, v78
	v_lshlrev_b32_e32 v4, 16, v70
	v_and_b32_e32 v5, 0xffff0000, v70
	v_sub_f32_e32 v20, v20, v84
	v_sub_f32_e32 v21, v21, v84
	v_mul_f32_e32 v20, v20, v85
	v_mul_f32_e32 v21, v21, v85
	v_fma_f32 v20, v20, v132, v148
	v_fma_f32 v21, v21, v133, v149
	v_fma_f32 v4, v20, s14, v4
	v_fma_f32 v5, v21, s14, v5
	v_lshlrev_b32_e32 v22, 16, v79
	v_and_b32_e32 v23, 0xffff0000, v79
	v_lshlrev_b32_e32 v6, 16, v71
	v_and_b32_e32 v7, 0xffff0000, v71
	v_sub_f32_e32 v22, v22, v84
	v_sub_f32_e32 v23, v23, v84
	v_mul_f32_e32 v22, v22, v85
	v_mul_f32_e32 v23, v23, v85
	v_fma_f32 v22, v22, v134, v150
	v_fma_f32 v23, v23, v135, v151
	v_fma_f32 v6, v22, s14, v6
	v_fma_f32 v7, v23, s14, v7
	v_lshlrev_b32_e32 v24, 16, v80
	v_and_b32_e32 v25, 0xffff0000, v80
	v_lshlrev_b32_e32 v8, 16, v72
	v_and_b32_e32 v9, 0xffff0000, v72
	v_sub_f32_e32 v24, v24, v84
	v_sub_f32_e32 v25, v25, v84
	v_mul_f32_e32 v24, v24, v85
	v_mul_f32_e32 v25, v25, v85
	v_fma_f32 v24, v24, v136, v152
	v_fma_f32 v25, v25, v137, v153
	v_fma_f32 v8, v24, s14, v8
	v_fma_f32 v9, v25, s14, v9
	v_lshlrev_b32_e32 v26, 16, v81
	v_and_b32_e32 v27, 0xffff0000, v81
	v_lshlrev_b32_e32 v10, 16, v73
	v_and_b32_e32 v11, 0xffff0000, v73
	v_sub_f32_e32 v26, v26, v84
	v_sub_f32_e32 v27, v27, v84
	v_mul_f32_e32 v26, v26, v85
	v_mul_f32_e32 v27, v27, v85
	v_fma_f32 v26, v26, v138, v154
	v_fma_f32 v27, v27, v139, v155
	v_fma_f32 v10, v26, s14, v10
	v_fma_f32 v11, v27, s14, v11
	v_lshlrev_b32_e32 v28, 16, v82
	v_and_b32_e32 v29, 0xffff0000, v82
	v_lshlrev_b32_e32 v12, 16, v74
	v_and_b32_e32 v13, 0xffff0000, v74
	v_sub_f32_e32 v28, v28, v84
	v_sub_f32_e32 v29, v29, v84
	v_mul_f32_e32 v28, v28, v85
	v_mul_f32_e32 v29, v29, v85
	v_fma_f32 v28, v28, v140, v156
	v_fma_f32 v29, v29, v141, v157
	v_fma_f32 v12, v28, s14, v12
	v_fma_f32 v13, v29, s14, v13
	v_lshlrev_b32_e32 v30, 16, v83
	v_and_b32_e32 v31, 0xffff0000, v83
	v_lshlrev_b32_e32 v14, 16, v75
	v_and_b32_e32 v15, 0xffff0000, v75
	v_sub_f32_e32 v30, v30, v84
	v_sub_f32_e32 v31, v31, v84
	v_mul_f32_e32 v30, v30, v85
	v_mul_f32_e32 v31, v31, v85
	v_fma_f32 v30, v30, v142, v158
	v_fma_f32 v31, v31, v143, v159
	v_fma_f32 v14, v30, s14, v14
	v_fma_f32 v15, v31, s14, v15
	v_add_f32_e32 v16, v0, v1
	v_add_f32_e32 v17, v2, v3
	v_add_f32_e32 v18, v4, v5
	v_add_f32_e32 v19, v6, v7
	v_add_f32_e32 v20, v8, v9
	v_add_f32_e32 v21, v10, v11
	v_add_f32_e32 v22, v12, v13
	v_add_f32_e32 v23, v14, v15
	v_add_f32_e32 v16, v16, v17
	v_add_f32_e32 v18, v18, v19
	v_add_f32_e32 v20, v20, v21
	v_add_f32_e32 v22, v22, v23
	v_add_f32_e32 v16, v16, v18
	v_add_f32_e32 v20, v20, v22
	v_add_f32_e32 v32, v16, v20
	v_mov_b32_e32 v34, v32
	s_nop 1
	v_add_f32_dpp v34, v32, v32 quad_perm:[1,0,3,2] row_mask:0xf bank_mask:0xf
	s_nop 1
	v_add_f32_dpp v34, v34, v34 quad_perm:[2,3,0,1] row_mask:0xf bank_mask:0xf
	s_nop 1
	v_add_f32_dpp v34, v34, v34 row_half_mirror row_mask:0xf bank_mask:0xf
	s_nop 1
	v_add_f32_dpp v34, v34, v34 row_mirror row_mask:0xf bank_mask:0xf
	s_nop 1
	v_add_f32_dpp v34, v34, v34 row_bcast:15 row_mask:0xa bank_mask:0xf
	s_nop 1
	v_add_f32_dpp v34, v34, v34 row_bcast:31 row_mask:0xc bank_mask:0xf
	s_nop 1
	v_readlane_b32 s0, v34, 63
	s_nop 0
	v_mov_b32_e32 v33, 0x3a800000
	v_mul_f32_e32 v33, s0, v33
	v_sub_f32_e32 v0, v0, v33
	v_sub_f32_e32 v1, v1, v33
	v_sub_f32_e32 v2, v2, v33
	v_sub_f32_e32 v3, v3, v33
	v_sub_f32_e32 v4, v4, v33
	v_sub_f32_e32 v5, v5, v33
	v_sub_f32_e32 v6, v6, v33
	v_sub_f32_e32 v7, v7, v33
	v_sub_f32_e32 v8, v8, v33
	v_sub_f32_e32 v9, v9, v33
	v_sub_f32_e32 v10, v10, v33
	v_sub_f32_e32 v11, v11, v33
	v_sub_f32_e32 v12, v12, v33
	v_sub_f32_e32 v13, v13, v33
	v_sub_f32_e32 v14, v14, v33
	v_sub_f32_e32 v15, v15, v33
	v_mul_f32_e32 v16, v0, v0
	v_fmac_f32_e32 v16, v1, v1
	v_mul_f32_e32 v17, v2, v2
	v_fmac_f32_e32 v17, v3, v3
	v_mul_f32_e32 v18, v4, v4
	v_fmac_f32_e32 v18, v5, v5
	v_mul_f32_e32 v19, v6, v6
	v_fmac_f32_e32 v19, v7, v7
	v_mul_f32_e32 v20, v8, v8
	v_fmac_f32_e32 v20, v9, v9
	v_mul_f32_e32 v21, v10, v10
	v_fmac_f32_e32 v21, v11, v11
	v_mul_f32_e32 v22, v12, v12
	v_fmac_f32_e32 v22, v13, v13
	v_mul_f32_e32 v23, v14, v14
	v_fmac_f32_e32 v23, v15, v15
	v_add_f32_e32 v16, v16, v17
	v_add_f32_e32 v18, v18, v19
	v_add_f32_e32 v20, v20, v21
	v_add_f32_e32 v22, v22, v23
	v_add_f32_e32 v16, v16, v18
	v_add_f32_e32 v20, v20, v22
	v_add_f32_e32 v32, v16, v20
	v_mov_b32_e32 v34, v32
	s_nop 1
	v_add_f32_dpp v34, v32, v32 quad_perm:[1,0,3,2] row_mask:0xf bank_mask:0xf
	s_nop 1
	v_add_f32_dpp v34, v34, v34 quad_perm:[2,3,0,1] row_mask:0xf bank_mask:0xf
	s_nop 1
	v_add_f32_dpp v34, v34, v34 row_half_mirror row_mask:0xf bank_mask:0xf
	s_nop 1
	v_add_f32_dpp v34, v34, v34 row_mirror row_mask:0xf bank_mask:0xf
	s_nop 1
	v_add_f32_dpp v34, v34, v34 row_bcast:15 row_mask:0xa bank_mask:0xf
	s_nop 1
	v_add_f32_dpp v34, v34, v34 row_bcast:31 row_mask:0xc bank_mask:0xf
	s_nop 1
	v_readlane_b32 s0, v34, 63
	s_nop 0
	v_mov_b32_e32 v33, 0x3a800000
	v_mov_b32_e32 v35, 0x3727c5ac
	v_fma_f32 v33, s0, v33, v35
	v_rsq_f32_e32 v33, v33
	s_nop 0
	v_mul_f32_e32 v0, v0, v33
	v_mul_f32_e32 v1, v1, v33
	v_mul_f32_e32 v2, v2, v33
	v_mul_f32_e32 v3, v3, v33
	v_fma_f32 v0, v0, v160, v176
	v_fma_f32 v1, v1, v161, v177
	v_fma_f32 v2, v2, v162, v178
	v_fma_f32 v3, v3, v163, v179
	v_mul_f32_e32 v4, v4, v33
	v_mul_f32_e32 v5, v5, v33
	v_mul_f32_e32 v6, v6, v33
	v_mul_f32_e32 v7, v7, v33
	v_fma_f32 v4, v4, v164, v180
	v_fma_f32 v5, v5, v165, v181
	v_fma_f32 v6, v6, v166, v182
	v_fma_f32 v7, v7, v167, v183
	v_mul_f32_e32 v8, v8, v33
	v_mul_f32_e32 v9, v9, v33
	v_mul_f32_e32 v10, v10, v33
	v_mul_f32_e32 v11, v11, v33
	v_fma_f32 v8, v8, v168, v184
	v_fma_f32 v9, v9, v169, v185
	v_fma_f32 v10, v10, v170, v186
	v_fma_f32 v11, v11, v171, v187
	v_mul_f32_e32 v12, v12, v33
	v_mul_f32_e32 v13, v13, v33
	v_mul_f32_e32 v14, v14, v33
	v_mul_f32_e32 v15, v15, v33
	v_fma_f32 v12, v12, v172, v188
	v_fma_f32 v13, v13, v173, v189
	v_fma_f32 v14, v14, v174, v190
	v_fma_f32 v15, v15, v175, v191
	global_store_dwordx4 v[238:239], v[0:3], off
	global_store_dwordx4 v[238:239], v[4:7], off offset:16
	global_store_dwordx4 v[238:239], v[8:11], off offset:2048
	global_store_dwordx4 v[238:239], v[12:15], off offset:2064
	s_mov_b32 s44, 0x800000
	s_mov_b32 s45, 0
	v_lshl_add_u64 v[238:239], v[238:239], 0, s[44:45]
	s_add_u32 s33, s33, 1
	global_load_dwordx4 v[68:71], v[232:233], off
	global_load_dwordx4 v[72:75], v[232:233], off offset:1024
	global_load_dwordx4 v[76:79], v[234:235], off
	global_load_dwordx4 v[80:83], v[234:235], off offset:1024
	global_load_dwordx2 v[84:85], v[236:237], off
	s_cmp_lt_u32 s33, 28
	s_cselect_b32 s44, s40, 0
	s_cselect_b32 s46, s42, 0
	s_mov_b32 s45, 0
	s_mov_b32 s47, 0
	v_lshl_add_u64 v[232:233], v[232:233], 0, s[44:45]
	v_lshl_add_u64 v[234:235], v[234:235], 0, s[44:45]
	v_lshl_add_u64 v[236:237], v[236:237], 0, s[46:47]
	s_waitcnt vmcnt(18)
	v_lshlrev_b32_e32 v16, 16, v96
	v_and_b32_e32 v17, 0xffff0000, v96
	v_lshlrev_b32_e32 v0, 16, v88
	v_and_b32_e32 v1, 0xffff0000, v88
	v_sub_f32_e32 v16, v16, v104
	v_sub_f32_e32 v17, v17, v104
	v_mul_f32_e32 v16, v16, v105
	v_mul_f32_e32 v17, v17, v105
	v_fma_f32 v16, v16, v128, v144
	v_fma_f32 v17, v17, v129, v145
	v_fma_f32 v0, v16, s14, v0
	v_fma_f32 v1, v17, s14, v1
	v_lshlrev_b32_e32 v18, 16, v97
	v_and_b32_e32 v19, 0xffff0000, v97
	v_lshlrev_b32_e32 v2, 16, v89
	v_and_b32_e32 v3, 0xffff0000, v89
	v_sub_f32_e32 v18, v18, v104
	v_sub_f32_e32 v19, v19, v104
	v_mul_f32_e32 v18, v18, v105
	v_mul_f32_e32 v19, v19, v105
	v_fma_f32 v18, v18, v130, v146
	v_fma_f32 v19, v19, v131, v147
	v_fma_f32 v2, v18, s14, v2
	v_fma_f32 v3, v19, s14, v3
	v_lshlrev_b32_e32 v20, 16, v98
	v_and_b32_e32 v21, 0xffff0000, v98
	v_lshlrev_b32_e32 v4, 16, v90
	v_and_b32_e32 v5, 0xffff0000, v90
	v_sub_f32_e32 v20, v20, v104
	v_sub_f32_e32 v21, v21, v104
	v_mul_f32_e32 v20, v20, v105
	v_mul_f32_e32 v21, v21, v105
	v_fma_f32 v20, v20, v132, v148
	v_fma_f32 v21, v21, v133, v149
	v_fma_f32 v4, v20, s14, v4
	v_fma_f32 v5, v21, s14, v5
	v_lshlrev_b32_e32 v22, 16, v99
	v_and_b32_e32 v23, 0xffff0000, v99
	v_lshlrev_b32_e32 v6, 16, v91
	v_and_b32_e32 v7, 0xffff0000, v91
	v_sub_f32_e32 v22, v22, v104
	v_sub_f32_e32 v23, v23, v104
	v_mul_f32_e32 v22, v22, v105
	v_mul_f32_e32 v23, v23, v105
	v_fma_f32 v22, v22, v134, v150
	v_fma_f32 v23, v23, v135, v151
	v_fma_f32 v6, v22, s14, v6
	v_fma_f32 v7, v23, s14, v7
	v_lshlrev_b32_e32 v24, 16, v100
	v_and_b32_e32 v25, 0xffff0000, v100
	v_lshlrev_b32_e32 v8, 16, v92
	v_and_b32_e32 v9, 0xffff0000, v92
	v_sub_f32_e32 v24, v24, v104
	v_sub_f32_e32 v25, v25, v104
	v_mul_f32_e32 v24, v24, v105
	v_mul_f32_e32 v25, v25, v105
	v_fma_f32 v24, v24, v136, v152
	v_fma_f32 v25, v25, v137, v153
	v_fma_f32 v8, v24, s14, v8
	v_fma_f32 v9, v25, s14, v9
	v_lshlrev_b32_e32 v26, 16, v101
	v_and_b32_e32 v27, 0xffff0000, v101
	v_lshlrev_b32_e32 v10, 16, v93
	v_and_b32_e32 v11, 0xffff0000, v93
	v_sub_f32_e32 v26, v26, v104
	v_sub_f32_e32 v27, v27, v104
	v_mul_f32_e32 v26, v26, v105
	v_mul_f32_e32 v27, v27, v105
	v_fma_f32 v26, v26, v138, v154
	v_fma_f32 v27, v27, v139, v155
	v_fma_f32 v10, v26, s14, v10
	v_fma_f32 v11, v27, s14, v11
	v_lshlrev_b32_e32 v28, 16, v102
	v_and_b32_e32 v29, 0xffff0000, v102
	v_lshlrev_b32_e32 v12, 16, v94
	v_and_b32_e32 v13, 0xffff0000, v94
	v_sub_f32_e32 v28, v28, v104
	v_sub_f32_e32 v29, v29, v104
	v_mul_f32_e32 v28, v28, v105
	v_mul_f32_e32 v29, v29, v105
	v_fma_f32 v28, v28, v140, v156
	v_fma_f32 v29, v29, v141, v157
	v_fma_f32 v12, v28, s14, v12
	v_fma_f32 v13, v29, s14, v13
	v_lshlrev_b32_e32 v30, 16, v103
	v_and_b32_e32 v31, 0xffff0000, v103
	v_lshlrev_b32_e32 v14, 16, v95
	v_and_b32_e32 v15, 0xffff0000, v95
	v_sub_f32_e32 v30, v30, v104
	v_sub_f32_e32 v31, v31, v104
	v_mul_f32_e32 v30, v30, v105
	v_mul_f32_e32 v31, v31, v105
	v_fma_f32 v30, v30, v142, v158
	v_fma_f32 v31, v31, v143, v159
	v_fma_f32 v14, v30, s14, v14
	v_fma_f32 v15, v31, s14, v15
	v_add_f32_e32 v16, v0, v1
	v_add_f32_e32 v17, v2, v3
	v_add_f32_e32 v18, v4, v5
	v_add_f32_e32 v19, v6, v7
	v_add_f32_e32 v20, v8, v9
	v_add_f32_e32 v21, v10, v11
	v_add_f32_e32 v22, v12, v13
	v_add_f32_e32 v23, v14, v15
	v_add_f32_e32 v16, v16, v17
	v_add_f32_e32 v18, v18, v19
	v_add_f32_e32 v20, v20, v21
	v_add_f32_e32 v22, v22, v23
	v_add_f32_e32 v16, v16, v18
	v_add_f32_e32 v20, v20, v22
	v_add_f32_e32 v32, v16, v20
	v_mov_b32_e32 v34, v32
	s_nop 1
	v_add_f32_dpp v34, v32, v32 quad_perm:[1,0,3,2] row_mask:0xf bank_mask:0xf
	s_nop 1
	v_add_f32_dpp v34, v34, v34 quad_perm:[2,3,0,1] row_mask:0xf bank_mask:0xf
	s_nop 1
	v_add_f32_dpp v34, v34, v34 row_half_mirror row_mask:0xf bank_mask:0xf
	s_nop 1
	v_add_f32_dpp v34, v34, v34 row_mirror row_mask:0xf bank_mask:0xf
	s_nop 1
	v_add_f32_dpp v34, v34, v34 row_bcast:15 row_mask:0xa bank_mask:0xf
	s_nop 1
	v_add_f32_dpp v34, v34, v34 row_bcast:31 row_mask:0xc bank_mask:0xf
	s_nop 1
	v_readlane_b32 s0, v34, 63
	s_nop 0
	v_mov_b32_e32 v33, 0x3a800000
	v_mul_f32_e32 v33, s0, v33
	v_sub_f32_e32 v0, v0, v33
	v_sub_f32_e32 v1, v1, v33
	v_sub_f32_e32 v2, v2, v33
	v_sub_f32_e32 v3, v3, v33
	v_sub_f32_e32 v4, v4, v33
	v_sub_f32_e32 v5, v5, v33
	v_sub_f32_e32 v6, v6, v33
	v_sub_f32_e32 v7, v7, v33
	v_sub_f32_e32 v8, v8, v33
	v_sub_f32_e32 v9, v9, v33
	v_sub_f32_e32 v10, v10, v33
	v_sub_f32_e32 v11, v11, v33
	v_sub_f32_e32 v12, v12, v33
	v_sub_f32_e32 v13, v13, v33
	v_sub_f32_e32 v14, v14, v33
	v_sub_f32_e32 v15, v15, v33
	v_mul_f32_e32 v16, v0, v0
	v_fmac_f32_e32 v16, v1, v1
	v_mul_f32_e32 v17, v2, v2
	v_fmac_f32_e32 v17, v3, v3
	v_mul_f32_e32 v18, v4, v4
	v_fmac_f32_e32 v18, v5, v5
	v_mul_f32_e32 v19, v6, v6
	v_fmac_f32_e32 v19, v7, v7
	v_mul_f32_e32 v20, v8, v8
	v_fmac_f32_e32 v20, v9, v9
	v_mul_f32_e32 v21, v10, v10
	v_fmac_f32_e32 v21, v11, v11
	v_mul_f32_e32 v22, v12, v12
	v_fmac_f32_e32 v22, v13, v13
	v_mul_f32_e32 v23, v14, v14
	v_fmac_f32_e32 v23, v15, v15
	v_add_f32_e32 v16, v16, v17
	v_add_f32_e32 v18, v18, v19
	v_add_f32_e32 v20, v20, v21
	v_add_f32_e32 v22, v22, v23
	v_add_f32_e32 v16, v16, v18
	v_add_f32_e32 v20, v20, v22
	v_add_f32_e32 v32, v16, v20
	v_mov_b32_e32 v34, v32
	s_nop 1
	v_add_f32_dpp v34, v32, v32 quad_perm:[1,0,3,2] row_mask:0xf bank_mask:0xf
	s_nop 1
	v_add_f32_dpp v34, v34, v34 quad_perm:[2,3,0,1] row_mask:0xf bank_mask:0xf
	s_nop 1
	v_add_f32_dpp v34, v34, v34 row_half_mirror row_mask:0xf bank_mask:0xf
	s_nop 1
	v_add_f32_dpp v34, v34, v34 row_mirror row_mask:0xf bank_mask:0xf
	s_nop 1
	v_add_f32_dpp v34, v34, v34 row_bcast:15 row_mask:0xa bank_mask:0xf
	s_nop 1
	v_add_f32_dpp v34, v34, v34 row_bcast:31 row_mask:0xc bank_mask:0xf
	s_nop 1
	v_readlane_b32 s0, v34, 63
	s_nop 0
	v_mov_b32_e32 v33, 0x3a800000
	v_mov_b32_e32 v35, 0x3727c5ac
	v_fma_f32 v33, s0, v33, v35
	v_rsq_f32_e32 v33, v33
	s_nop 0
	v_mul_f32_e32 v0, v0, v33
	v_mul_f32_e32 v1, v1, v33
	v_mul_f32_e32 v2, v2, v33
	v_mul_f32_e32 v3, v3, v33
	v_fma_f32 v0, v0, v160, v176
	v_fma_f32 v1, v1, v161, v177
	v_fma_f32 v2, v2, v162, v178
	v_fma_f32 v3, v3, v163, v179
	v_mul_f32_e32 v4, v4, v33
	v_mul_f32_e32 v5, v5, v33
	v_mul_f32_e32 v6, v6, v33
	v_mul_f32_e32 v7, v7, v33
	v_fma_f32 v4, v4, v164, v180
	v_fma_f32 v5, v5, v165, v181
	v_fma_f32 v6, v6, v166, v182
	v_fma_f32 v7, v7, v167, v183
	v_mul_f32_e32 v8, v8, v33
	v_mul_f32_e32 v9, v9, v33
	v_mul_f32_e32 v10, v10, v33
	v_mul_f32_e32 v11, v11, v33
	v_fma_f32 v8, v8, v168, v184
	v_fma_f32 v9, v9, v169, v185
	v_fma_f32 v10, v10, v170, v186
	v_fma_f32 v11, v11, v171, v187
	v_mul_f32_e32 v12, v12, v33
	v_mul_f32_e32 v13, v13, v33
	v_mul_f32_e32 v14, v14, v33
	v_mul_f32_e32 v15, v15, v33
	v_fma_f32 v12, v12, v172, v188
	v_fma_f32 v13, v13, v173, v189
	v_fma_f32 v14, v14, v174, v190
	v_fma_f32 v15, v15, v175, v191
	global_store_dwordx4 v[238:239], v[0:3], off
	global_store_dwordx4 v[238:239], v[4:7], off offset:16
	global_store_dwordx4 v[238:239], v[8:11], off offset:2048
	global_store_dwordx4 v[238:239], v[12:15], off offset:2064
	s_mov_b32 s44, 0x800000
	s_mov_b32 s45, 0
	v_lshl_add_u64 v[238:239], v[238:239], 0, s[44:45]
	s_add_u32 s33, s33, 1
	global_load_dwordx4 v[88:91], v[232:233], off
	global_load_dwordx4 v[92:95], v[232:233], off offset:1024
	global_load_dwordx4 v[96:99], v[234:235], off
	global_load_dwordx4 v[100:103], v[234:235], off offset:1024
	global_load_dwordx2 v[104:105], v[236:237], off
	s_cmp_lt_u32 s33, 28
	s_cselect_b32 s44, s40, 0
	s_cselect_b32 s46, s42, 0
	s_mov_b32 s45, 0
	s_mov_b32 s47, 0
	v_lshl_add_u64 v[232:233], v[232:233], 0, s[44:45]
	v_lshl_add_u64 v[234:235], v[234:235], 0, s[44:45]
	v_lshl_add_u64 v[236:237], v[236:237], 0, s[46:47]
	s_waitcnt vmcnt(18)
	v_lshlrev_b32_e32 v16, 16, v116
	v_and_b32_e32 v17, 0xffff0000, v116
	v_lshlrev_b32_e32 v0, 16, v108
	v_and_b32_e32 v1, 0xffff0000, v108
	v_sub_f32_e32 v16, v16, v124
	v_sub_f32_e32 v17, v17, v124
	v_mul_f32_e32 v16, v16, v125
	v_mul_f32_e32 v17, v17, v125
	v_fma_f32 v16, v16, v128, v144
	v_fma_f32 v17, v17, v129, v145
	v_fma_f32 v0, v16, s14, v0
	v_fma_f32 v1, v17, s14, v1
	v_lshlrev_b32_e32 v18, 16, v117
	v_and_b32_e32 v19, 0xffff0000, v117
	v_lshlrev_b32_e32 v2, 16, v109
	v_and_b32_e32 v3, 0xffff0000, v109
	v_sub_f32_e32 v18, v18, v124
	v_sub_f32_e32 v19, v19, v124
	v_mul_f32_e32 v18, v18, v125
	v_mul_f32_e32 v19, v19, v125
	v_fma_f32 v18, v18, v130, v146
	v_fma_f32 v19, v19, v131, v147
	v_fma_f32 v2, v18, s14, v2
	v_fma_f32 v3, v19, s14, v3
	v_lshlrev_b32_e32 v20, 16, v118
	v_and_b32_e32 v21, 0xffff0000, v118
	v_lshlrev_b32_e32 v4, 16, v110
	v_and_b32_e32 v5, 0xffff0000, v110
	v_sub_f32_e32 v20, v20, v124
	v_sub_f32_e32 v21, v21, v124
	v_mul_f32_e32 v20, v20, v125
	v_mul_f32_e32 v21, v21, v125
	v_fma_f32 v20, v20, v132, v148
	v_fma_f32 v21, v21, v133, v149
	v_fma_f32 v4, v20, s14, v4
	v_fma_f32 v5, v21, s14, v5
	v_lshlrev_b32_e32 v22, 16, v119
	v_and_b32_e32 v23, 0xffff0000, v119
	v_lshlrev_b32_e32 v6, 16, v111
	v_and_b32_e32 v7, 0xffff0000, v111
	v_sub_f32_e32 v22, v22, v124
	v_sub_f32_e32 v23, v23, v124
	v_mul_f32_e32 v22, v22, v125
	v_mul_f32_e32 v23, v23, v125
	v_fma_f32 v22, v22, v134, v150
	v_fma_f32 v23, v23, v135, v151
	v_fma_f32 v6, v22, s14, v6
	v_fma_f32 v7, v23, s14, v7
	v_lshlrev_b32_e32 v24, 16, v120
	v_and_b32_e32 v25, 0xffff0000, v120
	v_lshlrev_b32_e32 v8, 16, v112
	v_and_b32_e32 v9, 0xffff0000, v112
	v_sub_f32_e32 v24, v24, v124
	v_sub_f32_e32 v25, v25, v124
	v_mul_f32_e32 v24, v24, v125
	v_mul_f32_e32 v25, v25, v125
	v_fma_f32 v24, v24, v136, v152
	v_fma_f32 v25, v25, v137, v153
	v_fma_f32 v8, v24, s14, v8
	v_fma_f32 v9, v25, s14, v9
	v_lshlrev_b32_e32 v26, 16, v121
	v_and_b32_e32 v27, 0xffff0000, v121
	v_lshlrev_b32_e32 v10, 16, v113
	v_and_b32_e32 v11, 0xffff0000, v113
	v_sub_f32_e32 v26, v26, v124
	v_sub_f32_e32 v27, v27, v124
	v_mul_f32_e32 v26, v26, v125
	v_mul_f32_e32 v27, v27, v125
	v_fma_f32 v26, v26, v138, v154
	v_fma_f32 v27, v27, v139, v155
	v_fma_f32 v10, v26, s14, v10
	v_fma_f32 v11, v27, s14, v11
	v_lshlrev_b32_e32 v28, 16, v122
	v_and_b32_e32 v29, 0xffff0000, v122
	v_lshlrev_b32_e32 v12, 16, v114
	v_and_b32_e32 v13, 0xffff0000, v114
	v_sub_f32_e32 v28, v28, v124
	v_sub_f32_e32 v29, v29, v124
	v_mul_f32_e32 v28, v28, v125
	v_mul_f32_e32 v29, v29, v125
	v_fma_f32 v28, v28, v140, v156
	v_fma_f32 v29, v29, v141, v157
	v_fma_f32 v12, v28, s14, v12
	v_fma_f32 v13, v29, s14, v13
	v_lshlrev_b32_e32 v30, 16, v123
	v_and_b32_e32 v31, 0xffff0000, v123
	v_lshlrev_b32_e32 v14, 16, v115
	v_and_b32_e32 v15, 0xffff0000, v115
	v_sub_f32_e32 v30, v30, v124
	v_sub_f32_e32 v31, v31, v124
	v_mul_f32_e32 v30, v30, v125
	v_mul_f32_e32 v31, v31, v125
	v_fma_f32 v30, v30, v142, v158
	v_fma_f32 v31, v31, v143, v159
	v_fma_f32 v14, v30, s14, v14
	v_fma_f32 v15, v31, s14, v15
	v_add_f32_e32 v16, v0, v1
	v_add_f32_e32 v17, v2, v3
	v_add_f32_e32 v18, v4, v5
	v_add_f32_e32 v19, v6, v7
	v_add_f32_e32 v20, v8, v9
	v_add_f32_e32 v21, v10, v11
	v_add_f32_e32 v22, v12, v13
	v_add_f32_e32 v23, v14, v15
	v_add_f32_e32 v16, v16, v17
	v_add_f32_e32 v18, v18, v19
	v_add_f32_e32 v20, v20, v21
	v_add_f32_e32 v22, v22, v23
	v_add_f32_e32 v16, v16, v18
	v_add_f32_e32 v20, v20, v22
	v_add_f32_e32 v32, v16, v20
	v_mov_b32_e32 v34, v32
	s_nop 1
	v_add_f32_dpp v34, v32, v32 quad_perm:[1,0,3,2] row_mask:0xf bank_mask:0xf
	s_nop 1
	v_add_f32_dpp v34, v34, v34 quad_perm:[2,3,0,1] row_mask:0xf bank_mask:0xf
	s_nop 1
	v_add_f32_dpp v34, v34, v34 row_half_mirror row_mask:0xf bank_mask:0xf
	s_nop 1
	v_add_f32_dpp v34, v34, v34 row_mirror row_mask:0xf bank_mask:0xf
	s_nop 1
	v_add_f32_dpp v34, v34, v34 row_bcast:15 row_mask:0xa bank_mask:0xf
	s_nop 1
	v_add_f32_dpp v34, v34, v34 row_bcast:31 row_mask:0xc bank_mask:0xf
	s_nop 1
	v_readlane_b32 s0, v34, 63
	s_nop 0
	v_mov_b32_e32 v33, 0x3a800000
	v_mul_f32_e32 v33, s0, v33
	v_sub_f32_e32 v0, v0, v33
	v_sub_f32_e32 v1, v1, v33
	v_sub_f32_e32 v2, v2, v33
	v_sub_f32_e32 v3, v3, v33
	v_sub_f32_e32 v4, v4, v33
	v_sub_f32_e32 v5, v5, v33
	v_sub_f32_e32 v6, v6, v33
	v_sub_f32_e32 v7, v7, v33
	v_sub_f32_e32 v8, v8, v33
	v_sub_f32_e32 v9, v9, v33
	v_sub_f32_e32 v10, v10, v33
	v_sub_f32_e32 v11, v11, v33
	v_sub_f32_e32 v12, v12, v33
	v_sub_f32_e32 v13, v13, v33
	v_sub_f32_e32 v14, v14, v33
	v_sub_f32_e32 v15, v15, v33
	v_mul_f32_e32 v16, v0, v0
	v_fmac_f32_e32 v16, v1, v1
	v_mul_f32_e32 v17, v2, v2
	v_fmac_f32_e32 v17, v3, v3
	v_mul_f32_e32 v18, v4, v4
	v_fmac_f32_e32 v18, v5, v5
	v_mul_f32_e32 v19, v6, v6
	v_fmac_f32_e32 v19, v7, v7
	v_mul_f32_e32 v20, v8, v8
	v_fmac_f32_e32 v20, v9, v9
	v_mul_f32_e32 v21, v10, v10
	v_fmac_f32_e32 v21, v11, v11
	v_mul_f32_e32 v22, v12, v12
	v_fmac_f32_e32 v22, v13, v13
	v_mul_f32_e32 v23, v14, v14
	v_fmac_f32_e32 v23, v15, v15
	v_add_f32_e32 v16, v16, v17
	v_add_f32_e32 v18, v18, v19
	v_add_f32_e32 v20, v20, v21
	v_add_f32_e32 v22, v22, v23
	v_add_f32_e32 v16, v16, v18
	v_add_f32_e32 v20, v20, v22
	v_add_f32_e32 v32, v16, v20
	v_mov_b32_e32 v34, v32
	s_nop 1
	v_add_f32_dpp v34, v32, v32 quad_perm:[1,0,3,2] row_mask:0xf bank_mask:0xf
	s_nop 1
	v_add_f32_dpp v34, v34, v34 quad_perm:[2,3,0,1] row_mask:0xf bank_mask:0xf
	s_nop 1
	v_add_f32_dpp v34, v34, v34 row_half_mirror row_mask:0xf bank_mask:0xf
	s_nop 1
	v_add_f32_dpp v34, v34, v34 row_mirror row_mask:0xf bank_mask:0xf
	s_nop 1
	v_add_f32_dpp v34, v34, v34 row_bcast:15 row_mask:0xa bank_mask:0xf
	s_nop 1
	v_add_f32_dpp v34, v34, v34 row_bcast:31 row_mask:0xc bank_mask:0xf
	s_nop 1
	v_readlane_b32 s0, v34, 63
	s_nop 0
	v_mov_b32_e32 v33, 0x3a800000
	v_mov_b32_e32 v35, 0x3727c5ac
	v_fma_f32 v33, s0, v33, v35
	v_rsq_f32_e32 v33, v33
	s_nop 0
	v_mul_f32_e32 v0, v0, v33
	v_mul_f32_e32 v1, v1, v33
	v_mul_f32_e32 v2, v2, v33
	v_mul_f32_e32 v3, v3, v33
	v_fma_f32 v0, v0, v160, v176
	v_fma_f32 v1, v1, v161, v177
	v_fma_f32 v2, v2, v162, v178
	v_fma_f32 v3, v3, v163, v179
	v_mul_f32_e32 v4, v4, v33
	v_mul_f32_e32 v5, v5, v33
	v_mul_f32_e32 v6, v6, v33
	v_mul_f32_e32 v7, v7, v33
	v_fma_f32 v4, v4, v164, v180
	v_fma_f32 v5, v5, v165, v181
	v_fma_f32 v6, v6, v166, v182
	v_fma_f32 v7, v7, v167, v183
	v_mul_f32_e32 v8, v8, v33
	v_mul_f32_e32 v9, v9, v33
	v_mul_f32_e32 v10, v10, v33
	v_mul_f32_e32 v11, v11, v33
	v_fma_f32 v8, v8, v168, v184
	v_fma_f32 v9, v9, v169, v185
	v_fma_f32 v10, v10, v170, v186
	v_fma_f32 v11, v11, v171, v187
	v_mul_f32_e32 v12, v12, v33
	v_mul_f32_e32 v13, v13, v33
	v_mul_f32_e32 v14, v14, v33
	v_mul_f32_e32 v15, v15, v33
	v_fma_f32 v12, v12, v172, v188
	v_fma_f32 v13, v13, v173, v189
	v_fma_f32 v14, v14, v174, v190
	v_fma_f32 v15, v15, v175, v191
	global_store_dwordx4 v[238:239], v[0:3], off
	global_store_dwordx4 v[238:239], v[4:7], off offset:16
	global_store_dwordx4 v[238:239], v[8:11], off offset:2048
	global_store_dwordx4 v[238:239], v[12:15], off offset:2064
	s_mov_b32 s44, 0x800000
	s_mov_b32 s45, 0
	v_lshl_add_u64 v[238:239], v[238:239], 0, s[44:45]
	s_add_u32 s33, s33, 1
	s_cmp_lt_u32 s33, 32
	s_cbranch_scc1 .Lln2_loop
	s_endpgm
